# in-projection loop without s_setprio flips plus LDS-DMA staging groups issued inside the MFMA segments
# baseline (speedup 1.0000x reference)
; #define PG8_STAGE(bufoff, gbase, voff) do { _Pragma("unroll") for (int _i = 0; _i < 2; ++_i) \
;         __builtin_amdgcn_global_load_lds((const unsigned*)((const char*)(gbase) + (voff)[_i]), (LAS unsigned*)(lds + (bufoff) + ldsw + _i * 8192), 16, 0, 0); } while (0)
; #define PG8_LDA(dst, b, h) do { _Pragma("unroll") for (int m = 0; m < 4; ++m) _Pragma("unroll") for (int k = 0; k < 2; ++k) dst[m][k] = *(const LAS bf16x8*)(lds + PG8_SA(b, h) + aoff + m * 2048 + k * 1024); } while (0)
; #define PG8_LDB(dst, b, h) do { _Pragma("unroll") for (int n = 0; n < 2; ++n) _Pragma("unroll") for (int k = 0; k < 2; ++k) dst[n][k] = *(const LAS bf16x8*)(lds + PG8_SB(b, h) + boff + n * 2048 + k * 1024); } while (0)
; #define PG8_MMA(ai, bj, At, Bt) do { __builtin_amdgcn_s_setprio(1); _Pragma("unroll") for (int m = 0; m < 4; ++m) _Pragma("unroll") for (int n = 0; n < 2; ++n) _Pragma("unroll") for (int k = 0; k < 2; ++k) \
;         acc[ai][bj][m][n] = __builtin_amdgcn_mfma_f32_16x16x32_bf16(Bt[n][k], At[m][k], acc[ai][bj][m][n], 0, 0, 0); __builtin_amdgcn_s_setprio(0); } while (0)
; #define PG8_WAIT_V(n) asm volatile("s_waitcnt vmcnt(" #n ")" ::: "memory")
; #define PG8_WAIT_L(n) asm volatile("s_waitcnt lgkmcnt(" #n ")" ::: "memory")
; #define PG8_BAR __builtin_amdgcn_s_barrier()
; #define PG8_SCHED __builtin_amdgcn_sched_barrier(0)
; template <class Epi, class Sched>
; __device__ __forceinline__ void gemm_phase(LAS unsigned char* lds, const Gemm g, const Sched& S, const Epi& E, const int tid) {
;     ...
;             PG8_LDB(B0, 0, 0); PG8_LDB(B1, 0, 1); PG8_SCHED; PG8_LDA(At, 0, 0); PG8_STAGE(PG8_SA(1, 1), a1 + hstepA, voffA);
;             PG8_WAIT_V(8); PG8_WAIT_L(0); PG8_BAR; PG8_MMA(0, 0, At, B0); PG8_MMA(0, 1, At, B1); PG8_BAR; PG8_SCHED;
;             PG8_LDA(At, 0, 1); PG8_STAGE(PG8_SB(0, 0), b2, voffB); PG8_STAGE(PG8_SB(0, 1), b2 + hstepB, voffB); PG8_STAGE(PG8_SA(0, 0), a2, voffA);
;             PG8_WAIT_V(8); PG8_WAIT_L(0); PG8_BAR; PG8_MMA(1, 0, At, B0); PG8_MMA(1, 1, At, B1); PG8_BAR; PG8_SCHED;
.LBB0_347:
	s_add_u32 s24, s2, 0xfff80080
	s_addc_u32 s26, s3, -1
	s_add_i32 s31, 0, 0x10000
	s_cmp_eq_u32 s22, 28
	s_cselect_b32 s49, s15, s26
	s_cselect_b32 s48, s16, s24
	s_cselect_b32 s39, s11, s21
	s_cselect_b32 s38, s19, s20
	s_add_i32 s24, 0, 0x14000
	v_add_u32_e32 v140, s31, v158
	v_add_u32_e32 v154, s24, v158
	ds_read_b128 v[128:131], v140
	ds_read_b128 v[132:135], v140 offset:1024
	ds_read_b128 v[136:139], v140 offset:2048
	ds_read_b128 v[140:143], v140 offset:3072
	ds_read_b128 v[160:163], v154
	ds_read_b128 v[164:167], v154 offset:1024
	ds_read_b128 v[168:171], v154 offset:2048
	ds_read_b128 v[172:175], v154 offset:3072
	ds_read_b128 v[176:179], v159
	ds_read_b128 v[180:183], v159 offset:1024
	ds_read_b128 v[184:187], v159 offset:2048
	ds_read_b128 v[188:191], v159 offset:3072
	ds_read_b128 v[202:205], v159 offset:4096
	ds_read_b128 v[206:209], v159 offset:5120
	ds_read_b128 v[210:213], v159 offset:6144
	ds_read_b128 v[214:217], v159 offset:7168
	s_waitcnt vmcnt(6)
	s_waitcnt lgkmcnt(0)
	s_barrier
	s_waitcnt lgkmcnt(0)
	v_mfma_f32_16x16x32_bf16 v[124:127], v[128:131], v[176:179], v[124:127]
	v_mfma_f32_16x16x32_bf16 v[120:123], v[136:139], v[176:179], v[120:123]
	v_mfma_f32_16x16x32_bf16 v[108:111], v[128:131], v[184:187], v[108:111]
	v_mfma_f32_16x16x32_bf16 v[104:107], v[136:139], v[184:187], v[104:107]
	v_mfma_f32_16x16x32_bf16 v[92:95], v[128:131], v[202:205], v[92:95]
	v_mfma_f32_16x16x32_bf16 v[88:91], v[136:139], v[202:205], v[88:91]
	v_lshl_add_u64 v[154:155], s[2:3], 0, v[150:151]
	s_add_i32 m0, s45, 0xc000
	v_mfma_f32_16x16x32_bf16 v[76:79], v[128:131], v[210:213], v[76:79]
	global_load_lds_dwordx4 v[154:155], off
	v_mfma_f32_16x16x32_bf16 v[72:75], v[136:139], v[210:213], v[72:75]
	v_mfma_f32_16x16x32_bf16 v[124:127], v[132:135], v[180:183], v[124:127]
	v_mfma_f32_16x16x32_bf16 v[120:123], v[140:143], v[180:183], v[120:123]
	v_mfma_f32_16x16x32_bf16 v[108:111], v[132:135], v[188:191], v[108:111]
	v_mfma_f32_16x16x32_bf16 v[104:107], v[140:143], v[188:191], v[104:107]
	v_mfma_f32_16x16x32_bf16 v[92:95], v[132:135], v[206:209], v[92:95]
	v_mfma_f32_16x16x32_bf16 v[88:91], v[140:143], v[206:209], v[88:91]
	v_mfma_f32_16x16x32_bf16 v[76:79], v[132:135], v[214:217], v[76:79]
	v_mfma_f32_16x16x32_bf16 v[72:75], v[140:143], v[214:217], v[72:75]
	v_mfma_f32_16x16x32_bf16 v[116:119], v[160:163], v[176:179], v[116:119]
	v_mfma_f32_16x16x32_bf16 v[112:115], v[168:171], v[176:179], v[112:115]
	v_mfma_f32_16x16x32_bf16 v[100:103], v[160:163], v[184:187], v[100:103]
	v_mfma_f32_16x16x32_bf16 v[96:99], v[168:171], v[184:187], v[96:99]
	v_lshl_add_u64 v[154:155], s[2:3], 0, v[152:153]
	s_add_i32 m0, s45, 0xe000
	v_mfma_f32_16x16x32_bf16 v[84:87], v[160:163], v[202:205], v[84:87]
	global_load_lds_dwordx4 v[154:155], off
	v_mfma_f32_16x16x32_bf16 v[80:83], v[168:171], v[202:205], v[80:83]
	v_mfma_f32_16x16x32_bf16 v[68:71], v[160:163], v[210:213], v[68:71]
	v_mfma_f32_16x16x32_bf16 v[64:67], v[168:171], v[210:213], v[64:67]
	v_mfma_f32_16x16x32_bf16 v[116:119], v[164:167], v[180:183], v[116:119]
	v_mfma_f32_16x16x32_bf16 v[112:115], v[172:175], v[180:183], v[112:115]
	v_mfma_f32_16x16x32_bf16 v[100:103], v[164:167], v[188:191], v[100:103]
	v_mfma_f32_16x16x32_bf16 v[96:99], v[172:175], v[188:191], v[96:99]
	v_mfma_f32_16x16x32_bf16 v[84:87], v[164:167], v[206:209], v[84:87]
	v_mfma_f32_16x16x32_bf16 v[80:83], v[172:175], v[206:209], v[80:83]
	v_mfma_f32_16x16x32_bf16 v[68:71], v[164:167], v[214:217], v[68:71]
	v_mfma_f32_16x16x32_bf16 v[64:67], v[172:175], v[214:217], v[64:67]
	s_barrier
	s_add_i32 s26, s31, s25
	ds_read_b128 v[176:179], v159 offset:16384
	ds_read_b128 v[180:183], v159 offset:17408
	ds_read_b128 v[184:187], v159 offset:18432
	ds_read_b128 v[188:191], v159 offset:19456
	ds_read_b128 v[202:205], v159 offset:20480
	ds_read_b128 v[206:209], v159 offset:21504
	ds_read_b128 v[210:213], v159 offset:22528
	ds_read_b128 v[214:217], v159 offset:23552
	s_waitcnt vmcnt(2)
	s_waitcnt lgkmcnt(0)
	s_barrier
	s_waitcnt lgkmcnt(0)
	v_mfma_f32_16x16x32_bf16 v[60:63], v[128:131], v[176:179], v[60:63]
	v_mfma_f32_16x16x32_bf16 v[56:59], v[136:139], v[176:179], v[56:59]
	v_lshl_add_u64 v[154:155], s[38:39], 0, v[192:193]
	s_mov_b32 m0, s26
	v_mfma_f32_16x16x32_bf16 v[44:47], v[128:131], v[184:187], v[44:47]
	global_load_lds_dwordx4 v[154:155], off
	v_mfma_f32_16x16x32_bf16 v[40:43], v[136:139], v[184:187], v[40:43]
	v_mfma_f32_16x16x32_bf16 v[28:31], v[128:131], v[202:205], v[28:31]
	v_mfma_f32_16x16x32_bf16 v[24:27], v[136:139], v[202:205], v[24:27]
	v_mfma_f32_16x16x32_bf16 v[12:15], v[128:131], v[210:213], v[12:15]
	s_add_i32 m0, s26, 0x2000
	s_add_u32 s64, s38, 0x80000
	v_lshl_add_u64 v[218:219], s[38:39], 0, v[148:149]
	s_addc_u32 s65, s39, 0
	s_add_i32 s24, s24, s25
	v_mfma_f32_16x16x32_bf16 v[8:11], v[136:139], v[210:213], v[8:11]
	global_load_lds_dwordx4 v[218:219], off
	v_mfma_f32_16x16x32_bf16 v[60:63], v[132:135], v[180:183], v[60:63]
	v_mfma_f32_16x16x32_bf16 v[56:59], v[140:143], v[180:183], v[56:59]
	v_mfma_f32_16x16x32_bf16 v[44:47], v[132:135], v[188:191], v[44:47]
	v_mfma_f32_16x16x32_bf16 v[40:43], v[140:143], v[188:191], v[40:43]
	v_lshl_add_u64 v[220:221], s[64:65], 0, v[192:193]
	s_mov_b32 m0, s24
	v_lshl_add_u64 v[222:223], s[48:49], 0, v[146:147]
	v_mfma_f32_16x16x32_bf16 v[28:31], v[132:135], v[206:209], v[28:31]
	global_load_lds_dwordx4 v[220:221], off
	v_mfma_f32_16x16x32_bf16 v[24:27], v[140:143], v[206:209], v[24:27]
	v_mfma_f32_16x16x32_bf16 v[12:15], v[132:135], v[214:217], v[12:15]
	v_mfma_f32_16x16x32_bf16 v[8:11], v[140:143], v[214:217], v[8:11]
	v_mfma_f32_16x16x32_bf16 v[52:55], v[160:163], v[176:179], v[52:55]
	v_lshl_add_u64 v[220:221], s[64:65], 0, v[148:149]
	s_add_i32 m0, s24, 0x2000
	v_mfma_f32_16x16x32_bf16 v[48:51], v[168:171], v[176:179], v[48:51]
	global_load_lds_dwordx4 v[220:221], off
	v_mfma_f32_16x16x32_bf16 v[36:39], v[160:163], v[184:187], v[36:39]
	v_mfma_f32_16x16x32_bf16 v[32:35], v[168:171], v[184:187], v[32:35]
	v_mfma_f32_16x16x32_bf16 v[20:23], v[160:163], v[202:205], v[20:23]
	v_mfma_f32_16x16x32_bf16 v[16:19], v[168:171], v[202:205], v[16:19]
	v_lshl_add_u64 v[220:221], s[48:49], 0, v[144:145]
	s_mov_b32 m0, s45
	v_mfma_f32_16x16x32_bf16 v[4:7], v[160:163], v[210:213], v[4:7]
	global_load_lds_dwordx4 v[220:221], off
	v_mfma_f32_16x16x32_bf16 v[0:3], v[168:171], v[210:213], v[0:3]
	v_mfma_f32_16x16x32_bf16 v[52:55], v[164:167], v[180:183], v[52:55]
	v_mfma_f32_16x16x32_bf16 v[48:51], v[172:175], v[180:183], v[48:51]
	v_mfma_f32_16x16x32_bf16 v[36:39], v[164:167], v[188:191], v[36:39]
	s_mov_b32 m0, s47
	v_mfma_f32_16x16x32_bf16 v[32:35], v[172:175], v[188:191], v[32:35]
	global_load_lds_dwordx4 v[222:223], off
	v_mfma_f32_16x16x32_bf16 v[20:23], v[164:167], v[206:209], v[20:23]
	v_mfma_f32_16x16x32_bf16 v[16:19], v[172:175], v[206:209], v[16:19]
	v_mfma_f32_16x16x32_bf16 v[4:7], v[164:167], v[214:217], v[4:7]
	v_mfma_f32_16x16x32_bf16 v[0:3], v[172:175], v[214:217], v[0:3]
	s_barrier
; #define PG8_STAGE(bufoff, gbase, voff) do { _Pragma("unroll") for (int _i = 0; _i < 2; ++_i) \
;         __builtin_amdgcn_global_load_lds((const unsigned*)((const char*)(gbase) + (voff)[_i]), (LAS unsigned*)(lds + (bufoff) + ldsw + _i * 8192), 16, 0, 0); } while (0)
; #define PG8_LDA(dst, b, h) do { _Pragma("unroll") for (int m = 0; m < 4; ++m) _Pragma("unroll") for (int k = 0; k < 2; ++k) dst[m][k] = *(const LAS bf16x8*)(lds + PG8_SA(b, h) + aoff + m * 2048 + k * 1024); } while (0)
; #define PG8_LDB(dst, b, h) do { _Pragma("unroll") for (int n = 0; n < 2; ++n) _Pragma("unroll") for (int k = 0; k < 2; ++k) dst[n][k] = *(const LAS bf16x8*)(lds + PG8_SB(b, h) + boff + n * 2048 + k * 1024); } while (0)
; #define PG8_MMA(ai, bj, At, Bt) do { __builtin_amdgcn_s_setprio(1); _Pragma("unroll") for (int m = 0; m < 4; ++m) _Pragma("unroll") for (int n = 0; n < 2; ++n) _Pragma("unroll") for (int k = 0; k < 2; ++k) \
;         acc[ai][bj][m][n] = __builtin_amdgcn_mfma_f32_16x16x32_bf16(Bt[n][k], At[m][k], acc[ai][bj][m][n], 0, 0, 0); __builtin_amdgcn_s_setprio(0); } while (0)
; #define PG8_WAIT_V(n) asm volatile("s_waitcnt vmcnt(" #n ")" ::: "memory")
; #define PG8_WAIT_L(n) asm volatile("s_waitcnt lgkmcnt(" #n ")" ::: "memory")
; #define PG8_BAR __builtin_amdgcn_s_barrier()
; #define PG8_SCHED __builtin_amdgcn_sched_barrier(0)
; template <class Epi, class Sched>
; __device__ __forceinline__ void gemm_phase(LAS unsigned char* lds, const Gemm g, const Sched& S, const Epi& E, const int tid) {
;     ...
;             PG8_LDB(B0, 1, 0); PG8_LDB(B1, 1, 1); PG8_SCHED; PG8_LDA(At, 1, 0); PG8_STAGE(PG8_SA(0, 1), a2 + hstepA, voffA);
;             PG8_WAIT_V(8); PG8_WAIT_L(0); PG8_BAR; PG8_MMA(0, 0, At, B0); PG8_MMA(0, 1, At, B1); PG8_BAR; PG8_SCHED;
	s_add_i32 s24, 0, 0x18000
	s_add_i32 s26, 0, 0x1c000
	v_add_u32_e32 v140, s24, v158
	v_add_u32_e32 v172, s26, v158
	ds_read_b128 v[128:131], v140
	ds_read_b128 v[132:135], v140 offset:1024
	ds_read_b128 v[136:139], v140 offset:2048
	ds_read_b128 v[140:143], v140 offset:3072
	ds_read_b128 v[160:163], v172
	ds_read_b128 v[164:167], v172 offset:1024
	ds_read_b128 v[168:171], v172 offset:2048
	ds_read_b128 v[172:175], v172 offset:3072
	s_add_u32 s48, s48, 0x80000
	s_addc_u32 s49, s49, 0
	ds_read_b128 v[176:179], v159 offset:32768
	ds_read_b128 v[180:183], v159 offset:33792
	ds_read_b128 v[184:187], v159 offset:34816
	ds_read_b128 v[188:191], v159 offset:35840
	ds_read_b128 v[202:205], v159 offset:36864
	ds_read_b128 v[206:209], v159 offset:37888
	ds_read_b128 v[210:213], v159 offset:38912
	ds_read_b128 v[214:217], v159 offset:39936
	s_waitcnt vmcnt(6)
	s_waitcnt lgkmcnt(0)
	s_barrier
	s_waitcnt lgkmcnt(0)
	v_mfma_f32_16x16x32_bf16 v[124:127], v[128:131], v[176:179], v[124:127]
	v_mfma_f32_16x16x32_bf16 v[120:123], v[136:139], v[176:179], v[120:123]
	v_mfma_f32_16x16x32_bf16 v[108:111], v[128:131], v[184:187], v[108:111]
	v_mfma_f32_16x16x32_bf16 v[104:107], v[136:139], v[184:187], v[104:107]
	v_mfma_f32_16x16x32_bf16 v[92:95], v[128:131], v[202:205], v[92:95]
	v_mfma_f32_16x16x32_bf16 v[88:91], v[136:139], v[202:205], v[88:91]
	s_mov_b32 m0, s52
	v_lshl_add_u64 v[234:235], s[48:49], 0, v[144:145]
	v_mfma_f32_16x16x32_bf16 v[76:79], v[128:131], v[210:213], v[76:79]
	global_load_lds_dwordx4 v[234:235], off
	v_mfma_f32_16x16x32_bf16 v[72:75], v[136:139], v[210:213], v[72:75]
	v_mfma_f32_16x16x32_bf16 v[124:127], v[132:135], v[180:183], v[124:127]
	v_mfma_f32_16x16x32_bf16 v[120:123], v[140:143], v[180:183], v[120:123]
	v_mfma_f32_16x16x32_bf16 v[108:111], v[132:135], v[188:191], v[108:111]
	v_mfma_f32_16x16x32_bf16 v[104:107], v[140:143], v[188:191], v[104:107]
	v_mfma_f32_16x16x32_bf16 v[92:95], v[132:135], v[206:209], v[92:95]
	v_mfma_f32_16x16x32_bf16 v[88:91], v[140:143], v[206:209], v[88:91]
	v_mfma_f32_16x16x32_bf16 v[76:79], v[132:135], v[214:217], v[76:79]
	v_mfma_f32_16x16x32_bf16 v[72:75], v[140:143], v[214:217], v[72:75]
	v_mfma_f32_16x16x32_bf16 v[116:119], v[160:163], v[176:179], v[116:119]
	v_mfma_f32_16x16x32_bf16 v[112:115], v[168:171], v[176:179], v[112:115]
	v_mfma_f32_16x16x32_bf16 v[100:103], v[160:163], v[184:187], v[100:103]
	v_mfma_f32_16x16x32_bf16 v[96:99], v[168:171], v[184:187], v[96:99]
	v_lshl_add_u64 v[234:235], s[48:49], 0, v[146:147]
	s_mov_b32 m0, s53
	v_mfma_f32_16x16x32_bf16 v[84:87], v[160:163], v[202:205], v[84:87]
	global_load_lds_dwordx4 v[234:235], off
	v_mfma_f32_16x16x32_bf16 v[80:83], v[168:171], v[202:205], v[80:83]
	v_mfma_f32_16x16x32_bf16 v[68:71], v[160:163], v[210:213], v[68:71]
	v_mfma_f32_16x16x32_bf16 v[64:67], v[168:171], v[210:213], v[64:67]
	v_mfma_f32_16x16x32_bf16 v[116:119], v[164:167], v[180:183], v[116:119]
	v_mfma_f32_16x16x32_bf16 v[112:115], v[172:175], v[180:183], v[112:115]
	v_mfma_f32_16x16x32_bf16 v[100:103], v[164:167], v[188:191], v[100:103]
	v_mfma_f32_16x16x32_bf16 v[96:99], v[172:175], v[188:191], v[96:99]
	v_mfma_f32_16x16x32_bf16 v[84:87], v[164:167], v[206:209], v[84:87]
	v_mfma_f32_16x16x32_bf16 v[80:83], v[172:175], v[206:209], v[80:83]
	v_mfma_f32_16x16x32_bf16 v[68:71], v[164:167], v[214:217], v[68:71]
	v_mfma_f32_16x16x32_bf16 v[64:67], v[172:175], v[214:217], v[64:67]
	s_barrier
; #define PG8_STAGE(bufoff, gbase, voff) do { _Pragma("unroll") for (int _i = 0; _i < 2; ++_i) \
;         __builtin_amdgcn_global_load_lds((const unsigned*)((const char*)(gbase) + (voff)[_i]), (LAS unsigned*)(lds + (bufoff) + ldsw + _i * 8192), 16, 0, 0); } while (0)
; #define PG8_LDA(dst, b, h) do { _Pragma("unroll") for (int m = 0; m < 4; ++m) _Pragma("unroll") for (int k = 0; k < 2; ++k) dst[m][k] = *(const LAS bf16x8*)(lds + PG8_SA(b, h) + aoff + m * 2048 + k * 1024); } while (0)
; #define PG8_MMA(ai, bj, At, Bt) do { __builtin_amdgcn_s_setprio(1); _Pragma("unroll") for (int m = 0; m < 4; ++m) _Pragma("unroll") for (int n = 0; n < 2; ++n) _Pragma("unroll") for (int k = 0; k < 2; ++k) \
;         acc[ai][bj][m][n] = __builtin_amdgcn_mfma_f32_16x16x32_bf16(Bt[n][k], At[m][k], acc[ai][bj][m][n], 0, 0, 0); __builtin_amdgcn_s_setprio(0); } while (0)
; #define PG8_WAIT_V(n) asm volatile("s_waitcnt vmcnt(" #n ")" ::: "memory")
; #define PG8_WAIT_L(n) asm volatile("s_waitcnt lgkmcnt(" #n ")" ::: "memory")
; #define PG8_BAR __builtin_amdgcn_s_barrier()
; #define PG8_SCHED __builtin_amdgcn_sched_barrier(0)
; template <class Epi, class Sched>
; __device__ __forceinline__ void gemm_phase(LAS unsigned char* lds, const Gemm g, const Sched& S, const Epi& E, const int tid) {
;     ...
;             PG8_LDA(At, 1, 1); PG8_STAGE(PG8_SB(1, 0), b3, voffB); PG8_STAGE(PG8_SB(1, 1), b3 + hstepB, voffB); PG8_STAGE(PG8_SA(1, 0), a3, voffA);
;             PG8_WAIT_V(8); PG8_WAIT_L(0); PG8_BAR; PG8_MMA(1, 0, At, B0); PG8_MMA(1, 1, At, B1); PG8_BAR; PG8_SCHED;
;         }
	s_add_i32 s24, s24, s25
	ds_read_b128 v[176:179], v159 offset:49152
	ds_read_b128 v[180:183], v159 offset:50176
	ds_read_b128 v[184:187], v159 offset:51200
	ds_read_b128 v[188:191], v159 offset:52224
	ds_read_b128 v[202:205], v159 offset:53248
	ds_read_b128 v[206:209], v159 offset:54272
	ds_read_b128 v[210:213], v159 offset:55296
	ds_read_b128 v[214:217], v159 offset:56320
	s_waitcnt vmcnt(2)
	s_waitcnt lgkmcnt(0)
	s_barrier
	s_waitcnt lgkmcnt(0)
	v_mfma_f32_16x16x32_bf16 v[60:63], v[128:131], v[176:179], v[60:63]
	v_mfma_f32_16x16x32_bf16 v[56:59], v[136:139], v[176:179], v[56:59]
	v_lshl_add_u64 v[154:155], v[154:155], 0, s[34:35]
	s_mov_b32 m0, s24
	v_mfma_f32_16x16x32_bf16 v[44:47], v[128:131], v[184:187], v[44:47]
	global_load_lds_dwordx4 v[154:155], off
	v_mfma_f32_16x16x32_bf16 v[40:43], v[136:139], v[184:187], v[40:43]
	v_mfma_f32_16x16x32_bf16 v[28:31], v[128:131], v[202:205], v[28:31]
	v_mfma_f32_16x16x32_bf16 v[24:27], v[136:139], v[202:205], v[24:27]
	v_mfma_f32_16x16x32_bf16 v[12:15], v[128:131], v[210:213], v[12:15]
	s_add_i32 m0, s24, 0x2000
	s_add_u32 s38, s38, 0x80080
	v_lshl_add_u64 v[154:155], v[218:219], 0, s[34:35]
	s_addc_u32 s39, s39, 0
	s_add_i32 s24, s26, s25
	v_mfma_f32_16x16x32_bf16 v[8:11], v[136:139], v[210:213], v[8:11]
	global_load_lds_dwordx4 v[154:155], off
	v_mfma_f32_16x16x32_bf16 v[60:63], v[132:135], v[180:183], v[60:63]
	v_mfma_f32_16x16x32_bf16 v[56:59], v[140:143], v[180:183], v[56:59]
	v_mfma_f32_16x16x32_bf16 v[44:47], v[132:135], v[188:191], v[44:47]
	v_mfma_f32_16x16x32_bf16 v[40:43], v[140:143], v[188:191], v[40:43]
	v_lshl_add_u64 v[154:155], s[38:39], 0, v[192:193]
	s_mov_b32 m0, s24
	v_mfma_f32_16x16x32_bf16 v[28:31], v[132:135], v[206:209], v[28:31]
	global_load_lds_dwordx4 v[154:155], off
	v_mfma_f32_16x16x32_bf16 v[24:27], v[140:143], v[206:209], v[24:27]
	v_mfma_f32_16x16x32_bf16 v[12:15], v[132:135], v[214:217], v[12:15]
	v_mfma_f32_16x16x32_bf16 v[8:11], v[140:143], v[214:217], v[8:11]
	v_mfma_f32_16x16x32_bf16 v[52:55], v[160:163], v[176:179], v[52:55]
	v_lshl_add_u64 v[154:155], s[38:39], 0, v[148:149]
	s_add_i32 m0, s24, 0x2000
	v_mfma_f32_16x16x32_bf16 v[48:51], v[168:171], v[176:179], v[48:51]
	global_load_lds_dwordx4 v[154:155], off
	v_mfma_f32_16x16x32_bf16 v[36:39], v[160:163], v[184:187], v[36:39]
	v_mfma_f32_16x16x32_bf16 v[32:35], v[168:171], v[184:187], v[32:35]
	v_mfma_f32_16x16x32_bf16 v[20:23], v[160:163], v[202:205], v[20:23]
	v_mfma_f32_16x16x32_bf16 v[16:19], v[168:171], v[202:205], v[16:19]
	v_lshl_add_u64 v[154:155], v[220:221], 0, s[34:35]
	s_mov_b32 m0, s56
	v_mfma_f32_16x16x32_bf16 v[4:7], v[160:163], v[210:213], v[4:7]
	global_load_lds_dwordx4 v[154:155], off
	v_mfma_f32_16x16x32_bf16 v[0:3], v[168:171], v[210:213], v[0:3]
	v_mfma_f32_16x16x32_bf16 v[52:55], v[164:167], v[180:183], v[52:55]
	v_mfma_f32_16x16x32_bf16 v[48:51], v[172:175], v[180:183], v[48:51]
	v_mfma_f32_16x16x32_bf16 v[36:39], v[164:167], v[188:191], v[36:39]
	v_lshl_add_u64 v[154:155], v[222:223], 0, s[34:35]
	s_mov_b32 m0, s57
	v_mfma_f32_16x16x32_bf16 v[32:35], v[172:175], v[188:191], v[32:35]
	global_load_lds_dwordx4 v[154:155], off
	v_mfma_f32_16x16x32_bf16 v[20:23], v[164:167], v[206:209], v[20:23]
	v_mfma_f32_16x16x32_bf16 v[16:19], v[172:175], v[206:209], v[16:19]
	v_mfma_f32_16x16x32_bf16 v[4:7], v[164:167], v[214:217], v[4:7]
	v_mfma_f32_16x16x32_bf16 v[0:3], v[172:175], v[214:217], v[0:3]
	s_barrier
	s_add_i32 s22, s22, 2
	s_add_u32 s2, s2, 0x100
	s_addc_u32 s3, s3, 0
	s_add_u32 s20, s20, 0x100
	s_addc_u32 s21, s21, 0
	s_cmp_gt_u32 s22, 29
	s_cbranch_scc0 .LBB0_347
	s_and_b64 vcc, exec, s[8:9]
	s_cbranch_vccz .LBB0_350
	s_barrier
